# inproj1 q/k epilogue, second tile of each pair: rope cos/sin of row groups 1-7 prefetched in one batch into the registers freed by the unparked accumulators; loads become moves
# speedup vs baseline: 1.0096x; 1.0056x over previous
.LBB0_437:
	s_andn2_b64 vcc, exec, s[4:5]
	s_mov_b64 s[4:5], 0x1000
	s_cbranch_vccnz .LBB0_443
	s_cmp_lg_u32 s65, 0
	s_cbranch_scc0 .LBB0_447
	s_lshl_b64 s[58:59], s[0:1], 13
	s_cmp_eq_u32 s65, 1
	s_cselect_b64 s[56:57], -1, 0
	s_and_b64 s[0:1], s[56:57], exec
	s_cselect_b32 s1, s43, s45
	s_cselect_b32 s0, s42, s44
	v_mov_b32_e32 v120, v18
	v_mov_b32_e32 v121, v22
	v_mul_f32_e32 v122, v120, v120
	v_mul_f32_e32 v123, v121, v121
	global_load_dword v143, v192, s[0:1]
	global_load_dword v141, v192, s[0:1] offset:64
	global_load_dword v125, v192, s[0:1] offset:128
	global_load_dword v121, v192, s[0:1] offset:192
	global_load_dword v142, v192, s[0:1] offset:256
	global_load_dword v140, v192, s[0:1] offset:320
	v_and_b32_e32 v77, 64, v201
	v_xor_b32_e32 v76, 1, v201
	v_add_u32_e32 v77, 64, v77
	v_cmp_lt_i32_e32 vcc, v76, v77
	v_mov_b32_e32 v82, v41
	v_mov_b32_e32 v83, v45
	v_cndmask_b32_e32 v76, v201, v76, vcc
	v_lshlrev_b32_e32 v146, 2, v76
	v_xor_b32_e32 v76, 2, v201
	v_cmp_lt_i32_e32 vcc, v76, v77
	v_mul_f32_e32 v82, v82, v82
	v_mul_f32_e32 v83, v83, v83
	v_mul_f32_e32 v86, v36, v36
	v_mul_f32_e32 v87, v37, v37
	v_cndmask_b32_e32 v76, v201, v76, vcc
	v_lshlrev_b32_e32 v147, 2, v76
	v_xor_b32_e32 v76, 4, v201
	v_cmp_lt_i32_e32 vcc, v76, v77
	v_mov_b32_e32 v78, v48
	v_mov_b32_e32 v79, v52
	v_cndmask_b32_e32 v76, v201, v76, vcc
	v_lshlrev_b32_e32 v148, 2, v76
	v_xor_b32_e32 v76, 8, v201
	v_cmp_lt_i32_e32 vcc, v76, v77
	v_mov_b32_e32 v77, v44
	v_fma_f32 v86, v32, v32, v86
	v_fma_f32 v87, v33, v33, v87
	v_cndmask_b32_e32 v76, v201, v76, vcc
	v_lshlrev_b32_e32 v149, 2, v76
	v_mov_b32_e32 v76, v40
	v_mul_f32_e32 v76, v76, v76
	v_mul_f32_e32 v77, v77, v77
	v_mov_b32_e32 v88, v49
	v_mov_b32_e32 v89, v53
	v_mov_b32_e32 v126, v82
	v_mov_b32_e32 v127, v76
	v_mul_f32_e32 v78, v78, v78
	v_mul_f32_e32 v79, v79, v79
	v_mul_f32_e32 v88, v88, v88
	v_mul_f32_e32 v89, v89, v89
	v_pk_add_f32 v[86:87], v[86:87], v[126:127] op_sel:[1,0] op_sel_hi:[0,1]
	v_mov_b32_e32 v76, v83
	v_mov_b32_e32 v80, v56
	v_mov_b32_e32 v81, v60
	v_mov_b32_e32 v90, v57
	v_mov_b32_e32 v91, v61
	v_add_f32_e32 v76, v86, v76
	v_add_f32_e32 v77, v87, v77
	v_mov_b32_e32 v82, v88
	v_mov_b32_e32 v83, v78
	v_mul_f32_e32 v80, v80, v80
	v_mul_f32_e32 v81, v81, v81
	v_mul_f32_e32 v90, v90, v90
	v_mul_f32_e32 v91, v91, v91
	v_add_f32_e32 v76, v76, v82
	v_add_f32_e32 v77, v77, v83
	v_mov_b32_e32 v78, v89
	v_add_f32_e32 v76, v76, v78
	v_add_f32_e32 v77, v77, v79
	v_mov_b32_e32 v78, v90
	v_mov_b32_e32 v79, v80
	v_add_f32_e32 v76, v76, v78
	v_add_f32_e32 v77, v77, v79
	v_mov_b32_e32 v80, v91
	v_add_f32_e32 v76, v76, v80
	v_add_f32_e32 v77, v77, v81
	s_nop 1
	v_mov_b32_dpp v79, v77 quad_perm:[1,0,3,2] row_mask:0xf bank_mask:0xf
	v_mov_b32_dpp v78, v76 quad_perm:[1,0,3,2] row_mask:0xf bank_mask:0xf
	global_load_dword v124, v192, s[0:1] offset:384
	global_load_dword v120, v192, s[0:1] offset:448
	v_mov_b32_e32 v88, v3
	v_mov_b32_e32 v89, v11
	s_waitcnt lgkmcnt(0)
	v_add_f32_e32 v76, v76, v78
	v_add_f32_e32 v77, v77, v79
	s_nop 1
	v_mov_b32_dpp v79, v77 quad_perm:[2,3,0,1] row_mask:0xf bank_mask:0xf
	v_mov_b32_dpp v78, v76 quad_perm:[2,3,0,1] row_mask:0xf bank_mask:0xf
	v_mov_b32_e32 v92, v42
	v_mov_b32_e32 v93, v46
	v_mov_b32_e32 v98, v43
	v_mov_b32_e32 v99, v47
	s_waitcnt lgkmcnt(0)
	v_add_f32_e32 v76, v76, v78
	v_add_f32_e32 v77, v77, v79
	s_nop 1
	v_mov_b32_dpp v79, v77 row_half_mirror row_mask:0xf bank_mask:0xf
	v_mov_b32_dpp v78, v76 row_half_mirror row_mask:0xf bank_mask:0xf
	v_mul_f32_e32 v90, v88, v88
	v_mul_f32_e32 v91, v89, v89
	v_mov_b32_e32 v88, v27
	v_mov_b32_e32 v89, v31
	v_mul_f32_e32 v84, v38, v38
	v_mul_f32_e32 v85, v39, v39
	s_waitcnt lgkmcnt(0)
	v_add_f32_e32 v76, v76, v78
	v_add_f32_e32 v77, v77, v79
	s_nop 1
	v_mov_b32_dpp v79, v77 row_mirror row_mask:0xf bank_mask:0xf
	v_mov_b32_dpp v78, v76 row_mirror row_mask:0xf bank_mask:0xf
	v_mul_f32_e32 v92, v92, v92
	v_mul_f32_e32 v93, v93, v93
	v_mul_f32_e32 v98, v98, v98
	v_mul_f32_e32 v99, v99, v99
	v_fma_f32 v84, v34, v34, v84
	v_fma_f32 v85, v35, v35, v85
	v_mov_b32_e32 v94, v50
	s_waitcnt lgkmcnt(0)
	v_add_f32_e32 v76, v76, v78
	v_add_f32_e32 v77, v77, v79
	v_mov_b64_e32 v[78:79], s[52:53]
	v_fma_f32 v76, v76, s46, v78
	v_fma_f32 v77, v77, s46, v78
	v_mov_b32_e32 v95, v54
	v_mul_f32_e32 v126, 0x4b800000, v77
	v_cmp_gt_f32_e32 vcc, s60, v77
	v_cmp_gt_f32_e64 s[0:1], s60, v76
	v_mov_b32_e32 v100, v51
	v_cndmask_b32_e32 v77, v77, v126, vcc
	v_rsq_f32_e32 v126, v77
	v_mul_f32_e32 v77, 0x4b800000, v76
	v_cndmask_b32_e64 v76, v76, v77, s[0:1]
	v_rsq_f32_e32 v127, v76
	v_mul_f32_e32 v76, v88, v88
	v_mul_f32_e32 v77, v89, v89
	v_mul_f32_e32 v88, 0x45800000, v126
	v_mov_b32_e32 v101, v55
	v_cndmask_b32_e32 v126, v126, v88, vcc
	v_mov_b32_e32 v88, v98
	v_mov_b32_e32 v89, v92
	v_mul_f32_e32 v94, v94, v94
	v_mul_f32_e32 v95, v95, v95
	v_mul_f32_e32 v100, v100, v100
	v_mul_f32_e32 v101, v101, v101
	v_pk_add_f32 v[84:85], v[84:85], v[88:89] op_sel:[1,0] op_sel_hi:[0,1]
	v_mov_b32_e32 v92, v99
	v_mov_b32_e32 v96, v58
	v_mov_b32_e32 v97, v62
	v_mov_b32_e32 v102, v59
	v_mov_b32_e32 v103, v63
	v_add_f32_e32 v84, v84, v92
	v_add_f32_e32 v85, v85, v93
	v_mov_b32_e32 v88, v100
	v_mov_b32_e32 v89, v94
	v_mul_f32_e32 v96, v96, v96
	v_mul_f32_e32 v97, v97, v97
	v_mul_f32_e32 v102, v102, v102
	v_mul_f32_e32 v103, v103, v103
	v_add_f32_e32 v84, v84, v88
	v_add_f32_e32 v85, v85, v89
	v_mov_b32_e32 v94, v101
	v_add_f32_e32 v84, v84, v94
	v_add_f32_e32 v85, v85, v95
	v_mov_b32_e32 v88, v102
	v_mov_b32_e32 v89, v96
	v_add_f32_e32 v84, v84, v88
	v_add_f32_e32 v85, v85, v89
	v_mov_b32_e32 v96, v103
	v_add_f32_e32 v84, v84, v96
	v_add_f32_e32 v85, v85, v97
	s_nop 1
	v_mov_b32_dpp v89, v85 quad_perm:[1,0,3,2] row_mask:0xf bank_mask:0xf
	v_mov_b32_dpp v88, v84 quad_perm:[1,0,3,2] row_mask:0xf bank_mask:0xf
	v_mul_f32_e32 v144, 0x45800000, v127
	v_mov_b32_e32 v104, v16
	v_mov_b32_e32 v105, v20
	v_mov_b32_e32 v110, v17
	s_waitcnt lgkmcnt(0)
	v_add_f32_e32 v84, v84, v88
	v_add_f32_e32 v85, v85, v89
	s_nop 1
	v_mov_b32_dpp v89, v85 quad_perm:[2,3,0,1] row_mask:0xf bank_mask:0xf
	v_mov_b32_dpp v88, v84 quad_perm:[2,3,0,1] row_mask:0xf bank_mask:0xf
	v_mov_b32_e32 v111, v21
	v_cndmask_b32_e64 v96, v127, v144, s[0:1]
	v_mul_f32_e32 v104, v104, v104
	v_mul_f32_e32 v105, v105, v105
	v_mul_f32_e32 v110, v110, v110
	v_mul_f32_e32 v111, v111, v111
	v_mul_f32_e32 v114, v12, v12
	v_mul_f32_e32 v115, v13, v13
	s_waitcnt vmcnt(0)
	v_mul_f32_e32 v92, v96, v143
	v_mov_b32_e32 v106, v0
	v_mov_b32_e32 v107, v8
	v_fma_f32 v114, v4, v4, v114
	v_fma_f32 v115, v5, v5, v115
	v_mov_b32_e32 v116, v1
	v_mov_b32_e32 v117, v9
	v_mul_f32_e32 v127, v33, v92
	s_waitcnt lgkmcnt(0)
	v_add_f32_e32 v84, v84, v88
	v_add_f32_e32 v85, v85, v89
	v_mov_b32_e32 v92, v110
	v_mov_b32_e32 v93, v104
	v_mul_f32_e32 v106, v106, v106
	v_mul_f32_e32 v107, v107, v107
	v_mul_f32_e32 v116, v116, v116
	v_mul_f32_e32 v117, v117, v117
	v_mov_b32_dpp v89, v85 row_half_mirror row_mask:0xf bank_mask:0xf
	v_mov_b32_dpp v88, v84 row_half_mirror row_mask:0xf bank_mask:0xf
	v_add_f32_e32 v92, v115, v92
	v_add_f32_e32 v93, v114, v93
	v_mov_b32_e32 v104, v111
	v_mov_b32_e32 v108, v24
	v_mov_b32_e32 v109, v28
	v_mov_b32_e32 v118, v25
	v_mov_b32_e32 v119, v29
	v_add_f32_e32 v92, v92, v104
	v_add_f32_e32 v93, v93, v105
	v_mov_b32_e32 v94, v116
	v_mov_b32_e32 v95, v106
	v_mul_f32_e32 v108, v108, v108
	v_mul_f32_e32 v109, v109, v109
	v_mul_f32_e32 v118, v118, v118
	v_mul_f32_e32 v119, v119, v119
	v_add_f32_e32 v92, v92, v94
	v_add_f32_e32 v93, v93, v95
	v_mov_b32_e32 v106, v117
	v_add_f32_e32 v92, v92, v106
	v_add_f32_e32 v93, v93, v107
	v_mov_b32_e32 v94, v118
	v_mov_b32_e32 v95, v108
	v_add_f32_e32 v92, v92, v94
	v_add_f32_e32 v93, v93, v95
	v_mov_b32_e32 v108, v119
	s_waitcnt lgkmcnt(0)
	v_add_f32_e32 v84, v84, v88
	v_add_f32_e32 v85, v85, v89
	v_add_f32_e32 v92, v92, v108
	v_add_f32_e32 v93, v93, v109
	v_mov_b32_dpp v89, v85 row_mirror row_mask:0xf bank_mask:0xf
	v_mov_b32_dpp v88, v84 row_mirror row_mask:0xf bank_mask:0xf
	v_mov_b32_dpp v95, v93 quad_perm:[1,0,3,2] row_mask:0xf bank_mask:0xf
	v_mov_b32_dpp v94, v92 quad_perm:[1,0,3,2] row_mask:0xf bank_mask:0xf
	v_mul_f32_e32 v33, v96, v141
	v_mul_f32_e32 v150, v37, v33
	s_waitcnt lgkmcnt(2)
	v_add_f32_e32 v84, v84, v88
	v_add_f32_e32 v85, v85, v89
	v_mul_f32_e32 v33, v96, v125
	s_waitcnt lgkmcnt(0)
	v_add_f32_e32 v88, v92, v94
	v_add_f32_e32 v89, v93, v95
	s_nop 1
	v_mov_b32_dpp v93, v89 quad_perm:[2,3,0,1] row_mask:0xf bank_mask:0xf
	v_mov_b32_dpp v92, v88 quad_perm:[2,3,0,1] row_mask:0xf bank_mask:0xf
	v_fma_f32 v84, v84, s46, v78
	v_fma_f32 v85, v85, s46, v78
	v_mul_f32_e32 v151, v41, v33
	v_mul_f32_e32 v37, 0x4b800000, v85
	v_cmp_gt_f32_e32 vcc, s60, v85
	s_waitcnt lgkmcnt(0)
	v_add_f32_e32 v88, v88, v92
	v_add_f32_e32 v89, v89, v93
	s_nop 1
	v_mov_b32_dpp v93, v89 row_half_mirror row_mask:0xf bank_mask:0xf
	v_mov_b32_dpp v92, v88 row_half_mirror row_mask:0xf bank_mask:0xf
	v_mul_f32_e32 v41, 0x4b800000, v84
	v_cmp_gt_f32_e64 s[0:1], s60, v84
	v_cndmask_b32_e32 v37, v85, v37, vcc
	v_mul_f32_e32 v33, v96, v121
	s_waitcnt lgkmcnt(0)
	v_add_f32_e32 v88, v88, v92
	v_add_f32_e32 v89, v89, v93
	s_nop 1
	v_mov_b32_dpp v93, v89 row_mirror row_mask:0xf bank_mask:0xf
	v_mov_b32_dpp v92, v88 row_mirror row_mask:0xf bank_mask:0xf
	v_cndmask_b32_e64 v41, v84, v41, s[0:1]
	v_mul_f32_e32 v203, v45, v33
	v_mul_f32_e32 v33, v96, v142
	v_rsq_f32_e32 v37, v37
	s_waitcnt lgkmcnt(0)
	v_add_f32_e32 v84, v88, v92
	v_add_f32_e32 v85, v89, v93
	v_mul_f32_e32 v204, v49, v33
	v_fma_f32 v84, v84, s46, v78
	v_fma_f32 v85, v85, s46, v78
	v_mul_f32_e32 v33, v96, v140
	v_mul_f32_e32 v45, 0x4b800000, v85
	v_cmp_gt_f32_e64 s[4:5], s60, v85
	v_rsq_f32_e32 v41, v41
	v_mul_f32_e32 v104, v53, v33
	v_cndmask_b32_e64 v45, v85, v45, s[4:5]
	v_mul_f32_e32 v33, v96, v124
	v_rsq_f32_e32 v45, v45
	v_mul_f32_e32 v105, v57, v33
	v_mul_f32_e32 v33, v96, v120
	v_mul_f32_e32 v106, v61, v33
	v_mul_f32_e32 v33, 0x45800000, v37
	v_cndmask_b32_e32 v92, v37, v33, vcc
	v_mul_f32_e32 v33, 0x45800000, v41
	v_cndmask_b32_e64 v88, v41, v33, s[0:1]
	v_mul_f32_e32 v33, 0x45800000, v45
	v_cndmask_b32_e64 v108, v45, v33, s[4:5]
	v_mul_f32_e32 v33, 0x4b800000, v84
	v_cmp_gt_f32_e32 vcc, s60, v84
	v_mov_b32_e32 v86, v19
	v_mov_b32_e32 v87, v23
	v_cndmask_b32_e32 v33, v84, v33, vcc
	v_lshl_add_u64 v[84:85], s[58:59], 0, v[72:73]
	v_lshlrev_b64 v[144:145], 2, v[84:85]
	s_cmp_lg_u32 s89, 0
	s_cbranch_scc0 .Lmy_rp_nopf
	s_add_u32 s10, s6, 0x1000
	s_addc_u32 s11, s7, 0
	s_add_u32 s12, s8, 0x1000
	s_addc_u32 s13, s9, 0
	global_load_dword v188, v144, s[6:7] offset:256
	global_load_dword v189, v144, s[8:9] offset:256
	global_load_dword v190, v144, s[6:7] offset:320
	global_load_dword v191, v144, s[8:9] offset:320
	global_load_dword v208, v144, s[6:7] offset:384
	global_load_dword v209, v144, s[8:9] offset:384
	global_load_dword v210, v144, s[6:7] offset:448
	global_load_dword v211, v144, s[8:9] offset:448
	global_load_dword v232, v144, s[6:7] offset:512
	global_load_dword v233, v144, s[8:9] offset:512
	global_load_dword v234, v144, s[6:7] offset:576
	global_load_dword v235, v144, s[8:9] offset:576
	global_load_dword v236, v144, s[6:7] offset:640
	global_load_dword v237, v144, s[8:9] offset:640
	global_load_dword v238, v144, s[6:7] offset:704
	global_load_dword v239, v144, s[8:9] offset:704
	global_load_dword v240, v144, s[6:7] offset:768
	global_load_dword v241, v144, s[8:9] offset:768
	global_load_dword v242, v144, s[6:7] offset:832
	global_load_dword v243, v144, s[8:9] offset:832
	global_load_dword v248, v144, s[6:7] offset:896
	global_load_dword v249, v144, s[8:9] offset:896
	global_load_dword v250, v144, s[6:7] offset:960
	global_load_dword v251, v144, s[8:9] offset:960
	global_load_dword v252, v144, s[10:11]
	global_load_dword v253, v144, s[12:13]
	global_load_dword v254, v144, s[10:11] offset:64
	global_load_dword v255, v144, s[12:13] offset:64
	global_load_dword v66, v144, s[10:11] offset:128
	global_load_dword v67, v144, s[12:13] offset:128
	global_load_dword v68, v144, s[10:11] offset:192
	global_load_dword v69, v144, s[12:13] offset:192
	global_load_dword v71, v144, s[10:11] offset:256
	global_load_dword v74, v144, s[12:13] offset:256
	global_load_dword v75, v144, s[10:11] offset:320
	global_load_dword v160, v144, s[12:13] offset:320
	global_load_dword v161, v144, s[10:11] offset:384
	global_load_dword v162, v144, s[12:13] offset:384
	global_load_dword v185, v144, s[10:11] offset:448
	global_load_dword v186, v144, s[12:13] offset:448
	global_load_dword v187, v144, s[10:11] offset:512
	global_load_dword v207, v144, s[12:13] offset:512
	global_load_dword v212, v144, s[10:11] offset:576
	global_load_dword v213, v144, s[12:13] offset:576
	global_load_dword v214, v144, s[10:11] offset:640
	global_load_dword v216, v144, s[12:13] offset:640
	global_load_dword v218, v144, s[10:11] offset:704
	global_load_dword v220, v144, s[12:13] offset:704
	global_load_dword v222, v144, s[10:11] offset:768
	global_load_dword v224, v144, s[12:13] offset:768
	global_load_dword v226, v144, s[10:11] offset:832
	global_load_dword v228, v144, s[12:13] offset:832
	global_load_dword v230, v144, s[10:11] offset:896
	global_load_dword v231, v144, s[12:13] offset:896
	global_load_dword v244, v144, s[10:11] offset:960
	global_load_dword v245, v144, s[12:13] offset:960
.Lmy_rp_nopf:
	v_lshl_add_u64 v[84:85], s[6:7], 0, v[144:145]
	v_lshl_add_u64 v[94:95], s[8:9], 0, v[144:145]
	global_load_dword v85, v[84:85], off
	s_nop 0
	global_load_dword v84, v[94:95], off
	v_or_b32_e32 v94, 64, v144
	v_mov_b32_e32 v95, v145
	v_lshl_add_u64 v[96:97], s[6:7], 0, v[94:95]
	v_lshl_add_u64 v[94:95], s[8:9], 0, v[94:95]
	global_load_dword v97, v[96:97], off
	s_nop 0
	global_load_dword v96, v[94:95], off
	v_or_b32_e32 v98, 0x80, v144
	v_mov_b32_e32 v99, v145
	v_lshl_add_u64 v[100:101], s[6:7], 0, v[98:99]
	v_lshl_add_u64 v[98:99], s[8:9], 0, v[98:99]
	global_load_dword v101, v[100:101], off
	s_nop 0
	global_load_dword v100, v[98:99], off
	v_or_b32_e32 v98, 0xc0, v144
	v_mov_b32_e32 v99, v145
	v_lshl_add_u64 v[102:103], s[6:7], 0, v[98:99]
	v_lshl_add_u64 v[98:99], s[8:9], 0, v[98:99]
	global_load_dword v103, v[102:103], off
	s_nop 0
	global_load_dword v102, v[98:99], off
	v_mul_f32_e32 v112, v14, v14
	v_mul_f32_e32 v113, v15, v15
	v_mul_f32_e32 v86, v86, v86
	v_mul_f32_e32 v87, v87, v87
	v_fma_f32 v112, v6, v6, v112
	v_fma_f32 v113, v7, v7, v113
	v_mov_b32_e32 v80, v2
	v_mov_b32_e32 v81, v10
	v_mov_b32_e32 v94, v86
	v_mov_b32_e32 v95, v122
	v_mul_f32_e32 v80, v80, v80
	v_mul_f32_e32 v81, v81, v81
	v_add_f32_e32 v94, v113, v94
	v_add_f32_e32 v95, v112, v95
	v_mov_b32_e32 v122, v87
	v_mov_b32_e32 v82, v26
	v_mov_b32_e32 v83, v30
	v_add_f32_e32 v86, v94, v122
	v_add_f32_e32 v87, v95, v123
	v_mov_b32_e32 v94, v90
	v_mov_b32_e32 v95, v80
	v_mul_f32_e32 v82, v82, v82
	v_mul_f32_e32 v83, v83, v83
	v_add_f32_e32 v86, v86, v94
	v_add_f32_e32 v87, v87, v95
	v_mov_b32_e32 v80, v91
	v_add_f32_e32 v80, v86, v80
	v_add_f32_e32 v81, v87, v81
	v_mov_b32_e32 v86, v76
	v_mov_b32_e32 v87, v82
	v_add_f32_e32 v80, v80, v86
	v_add_f32_e32 v81, v81, v87
	v_mov_b32_e32 v82, v77
	v_add_f32_e32 v76, v80, v82
	v_add_f32_e32 v77, v81, v83
	s_nop 1
	v_mov_b32_dpp v81, v77 quad_perm:[1,0,3,2] row_mask:0xf bank_mask:0xf
	v_mov_b32_dpp v80, v76 quad_perm:[1,0,3,2] row_mask:0xf bank_mask:0xf
	v_rsq_f32_e32 v33, v33
	v_mov_b32_e32 v49, v32
	v_mov_b32_e32 v53, v36
	v_mov_b32_e32 v57, v40
	s_waitcnt lgkmcnt(0)
	v_add_f32_e32 v76, v76, v80
	v_add_f32_e32 v77, v77, v81
	s_nop 1
	v_mov_b32_dpp v81, v77 quad_perm:[2,3,0,1] row_mask:0xf bank_mask:0xf
	v_mov_b32_dpp v80, v76 quad_perm:[2,3,0,1] row_mask:0xf bank_mask:0xf
	v_mul_f32_e32 v37, 0x45800000, v33
	v_cndmask_b32_e32 v33, v33, v37, vcc
	v_mul_f32_e32 v37, v33, v143
	v_mul_f32_e32 v41, v5, v37
	s_waitcnt lgkmcnt(0)
	v_add_f32_e32 v76, v76, v80
	v_add_f32_e32 v77, v77, v81
	s_nop 1
	v_mov_b32_dpp v81, v77 row_half_mirror row_mask:0xf bank_mask:0xf
	v_mov_b32_dpp v80, v76 row_half_mirror row_mask:0xf bank_mask:0xf
	v_mul_f32_e32 v5, v33, v141
	v_mul_f32_e32 v45, v13, v5
	v_mul_f32_e32 v5, v33, v125
	v_mul_f32_e32 v5, v17, v5
	s_waitcnt lgkmcnt(0)
	v_add_f32_e32 v76, v76, v80
	v_add_f32_e32 v77, v77, v81
	s_nop 1
	v_mov_b32_dpp v81, v77 row_mirror row_mask:0xf bank_mask:0xf
	v_mov_b32_dpp v80, v76 row_mirror row_mask:0xf bank_mask:0xf
	v_mul_f32_e32 v13, v33, v121
	v_mul_f32_e32 v17, v33, v142
	v_mul_f32_e32 v13, v21, v13
	v_mul_f32_e32 v21, v1, v17
	v_mul_f32_e32 v1, v33, v140
	s_waitcnt lgkmcnt(0)
	v_add_f32_e32 v76, v76, v80
	v_add_f32_e32 v77, v77, v81
	v_mul_f32_e32 v109, v9, v1
	v_mul_f32_e32 v1, v33, v124
	v_fma_f32 v76, v76, s46, v78
	v_fma_f32 v77, v77, s46, v78
	v_mul_f32_e32 v17, v25, v1
	v_mul_f32_e32 v9, 0x4b800000, v77
	v_cmp_gt_f32_e32 vcc, s60, v77
	v_mul_f32_e32 v25, 0x4b800000, v76
	v_cmp_gt_f32_e64 s[0:1], s60, v76
	v_cndmask_b32_e32 v9, v77, v9, vcc
	v_mul_f32_e32 v1, v33, v120
	v_cndmask_b32_e64 v25, v76, v25, s[0:1]
	v_mul_f32_e32 v76, v126, v142
	v_mul_f32_e32 v77, v126, v143
	v_mul_f32_e32 v32, v48, v76
	v_mul_f32_e32 v33, v49, v77
	s_waitcnt vmcnt(7)
	v_mov_b32_e32 v76, v85
	s_waitcnt vmcnt(6)
	v_mov_b32_e32 v77, v84
	v_rsq_f32_e32 v9, v9
	v_mul_f32_e32 v48, v32, v84
	v_mul_f32_e32 v49, v33, v85
	v_mul_f32_e32 v32, v32, v76
	v_mul_f32_e32 v33, v33, v77
	v_mul_f32_e32 v76, v126, v140
	v_mul_f32_e32 v77, v126, v141
	v_rsq_f32_e32 v25, v25
	v_mul_f32_e32 v36, v52, v76
	v_mul_f32_e32 v37, v53, v77
	s_waitcnt vmcnt(5)
	v_mov_b32_e32 v76, v97
	s_waitcnt vmcnt(4)
	v_mov_b32_e32 v77, v96
	v_mul_f32_e32 v52, v36, v96
	v_mul_f32_e32 v53, v37, v97
	v_mul_f32_e32 v36, v36, v76
	v_mul_f32_e32 v37, v37, v77
	v_mul_f32_e32 v76, v126, v124
	v_mul_f32_e32 v77, v126, v125
	v_mul_f32_e32 v56, v56, v76
	v_mul_f32_e32 v57, v57, v77
	s_waitcnt vmcnt(3)
	v_mov_b32_e32 v78, v101
	s_waitcnt vmcnt(2)
	v_mov_b32_e32 v79, v100
	v_mul_f32_e32 v110, v29, v1
	v_mul_f32_e32 v1, 0x45800000, v9
	v_mul_f32_e32 v76, v56, v100
	v_mul_f32_e32 v77, v57, v101
	v_mul_f32_e32 v56, v56, v78
	v_mul_f32_e32 v57, v57, v79
	v_mul_f32_e32 v78, v126, v120
	v_mul_f32_e32 v79, v126, v121
	v_mov_b32_e32 v61, v44
	v_cndmask_b32_e32 v148, v9, v1, vcc
	v_mul_f32_e32 v1, 0x45800000, v25
	v_mul_f32_e32 v60, v60, v78
	v_mul_f32_e32 v61, v61, v79
	v_cndmask_b32_e64 v146, v25, v1, s[0:1]
	s_waitcnt vmcnt(0)
	v_mul_f32_e32 v78, v60, v102
	v_mul_f32_e32 v79, v61, v103
	v_mov_b32_e32 v80, v103
	v_mov_b32_e32 v81, v102
	v_cndmask_b32_e64 v64, v202, 1.0, s[56:57]
	v_mul_f32_e32 v60, v60, v80
	v_mul_f32_e32 v61, v61, v81
	s_cmp_lg_u32 s89, 0
	s_cbranch_scc1 .Lmy_rp1_p2
	v_or_b32_e32 v80, 0x100, v144
	v_mov_b32_e32 v81, v145
	v_lshl_add_u64 v[82:83], s[6:7], 0, v[80:81]
	v_lshl_add_u64 v[80:81], s[8:9], 0, v[80:81]
	global_load_dword v1, v[82:83], off
	global_load_dword v9, v[80:81], off
	v_or_b32_e32 v80, 0x140, v144
	v_mov_b32_e32 v81, v145
	v_lshl_add_u64 v[82:83], s[6:7], 0, v[80:81]
	v_lshl_add_u64 v[80:81], s[8:9], 0, v[80:81]
	v_or_b32_e32 v84, 0x180, v144
	v_mov_b32_e32 v85, v145
	v_lshl_add_u64 v[86:87], s[6:7], 0, v[84:85]
	v_lshl_add_u64 v[84:85], s[8:9], 0, v[84:85]
	global_load_dword v25, v[82:83], off
	global_load_dword v29, v[80:81], off
	global_load_dword v40, v[86:87], off
	global_load_dword v44, v[84:85], off
	v_or_b32_e32 v80, 0x1c0, v144
	v_mov_b32_e32 v81, v145
	v_lshl_add_u64 v[82:83], s[6:7], 0, v[80:81]
	v_lshl_add_u64 v[80:81], s[8:9], 0, v[80:81]
	global_load_dword v89, v[82:83], off
	global_load_dword v93, v[80:81], off
	s_branch .Lmy_rp1_j
.Lmy_rp1_p2:
	s_waitcnt vmcnt(0)
	v_or_b32_e32 v80, 0x100, v144
	v_mov_b32_e32 v81, v145
	v_lshl_add_u64 v[82:83], s[6:7], 0, v[80:81]
	v_lshl_add_u64 v[80:81], s[8:9], 0, v[80:81]
	v_mov_b32_e32 v1, v188
	v_mov_b32_e32 v9, v189
	v_or_b32_e32 v80, 0x140, v144
	v_mov_b32_e32 v81, v145
	v_lshl_add_u64 v[82:83], s[6:7], 0, v[80:81]
	v_lshl_add_u64 v[80:81], s[8:9], 0, v[80:81]
	v_or_b32_e32 v84, 0x180, v144
	v_mov_b32_e32 v85, v145
	v_lshl_add_u64 v[86:87], s[6:7], 0, v[84:85]
	v_lshl_add_u64 v[84:85], s[8:9], 0, v[84:85]
	v_mov_b32_e32 v25, v190
	v_mov_b32_e32 v29, v191
	v_mov_b32_e32 v40, v208
	v_mov_b32_e32 v44, v209
	v_or_b32_e32 v80, 0x1c0, v144
	v_mov_b32_e32 v81, v145
	v_lshl_add_u64 v[82:83], s[6:7], 0, v[80:81]
	v_lshl_add_u64 v[80:81], s[8:9], 0, v[80:81]
	v_mov_b32_e32 v89, v210
	v_mov_b32_e32 v93, v211
.Lmy_rp1_j:
	v_mov_b32_e32 v82, v33
	v_mov_b32_e32 v84, v37
	v_mov_b32_e32 v80, v49
	v_mov_b32_e32 v86, v53
	v_mov_b32_e32 v90, v77
	v_mov_b32_e32 v94, v57
	v_mov_b32_e32 v96, v79
	v_mov_b32_e32 v98, v61
	s_waitcnt vmcnt(7)
	v_mul_f32_e32 v33, v204, v1
	s_waitcnt vmcnt(6)
	v_mul_f32_e32 v83, v127, v9
	v_mul_f32_e32 v81, v127, v1
	v_mul_f32_e32 v49, v204, v9
	v_add_f32_e32 v32, v32, v82
	v_add_f32_e32 v33, v33, v83
	v_add_f32_e64 v48, v80, -v48
	v_add_f32_e64 v49, v81, -v49
	s_waitcnt vmcnt(5)
	v_mul_f32_e32 v37, v104, v25
	s_waitcnt vmcnt(4)
	v_mul_f32_e32 v85, v150, v29
	v_mul_f32_e32 v87, v150, v25
	v_mul_f32_e32 v53, v104, v29
	s_waitcnt vmcnt(3)
	v_mul_f32_e32 v91, v151, v40
	s_waitcnt vmcnt(2)
	v_mul_f32_e32 v77, v105, v44
	v_mul_f32_e32 v95, v151, v44
	v_mul_f32_e32 v57, v105, v40
	s_waitcnt vmcnt(1)
	v_mul_f32_e32 v97, v203, v89
	s_waitcnt vmcnt(0)
	v_mul_f32_e32 v79, v106, v93
	v_mul_f32_e32 v99, v203, v93
	v_mul_f32_e32 v61, v106, v89
	v_add_f32_e32 v36, v36, v84
	v_add_f32_e32 v37, v37, v85
	v_add_f32_e32 v56, v56, v94
	v_add_f32_e32 v57, v57, v95
	v_add_f32_e32 v60, v60, v98
	v_add_f32_e32 v61, v61, v99
	v_mul_f32_e32 v84, v64, v32
	v_mul_f32_e32 v85, v64, v33
	v_add_f32_e64 v32, v86, -v52
	v_add_f32_e64 v33, v87, -v53
	v_mul_f32_e32 v86, v64, v36
	v_mul_f32_e32 v87, v64, v37
	v_add_f32_e64 v36, v90, -v76
	v_add_f32_e64 v37, v91, -v77
	v_add_f32_e64 v52, v96, -v78
	v_add_f32_e64 v53, v97, -v79
	v_mul_f32_e32 v90, v64, v56
	v_mul_f32_e32 v91, v64, v57
	v_mul_f32_e32 v76, v64, v48
	v_mul_f32_e32 v77, v64, v49
	v_mul_f32_e32 v78, v64, v32
	v_mul_f32_e32 v79, v64, v33
	v_mul_f32_e32 v80, v64, v36
	v_mul_f32_e32 v81, v64, v37
	v_mul_f32_e32 v82, v64, v52
	v_mul_f32_e32 v83, v64, v53
	v_mul_f32_e32 v94, v64, v60
	v_mul_f32_e32 v95, v64, v61
	s_cmp_lg_u32 s89, 0
	s_cbranch_scc1 .Lmy_rp2_p2
	v_or_b32_e32 v32, 0x200, v144
	v_mov_b32_e32 v33, v145
	v_or_b32_e32 v48, 0x240, v144
	v_mov_b32_e32 v49, v145
	v_lshl_add_u64 v[36:37], s[6:7], 0, v[32:33]
	v_lshl_add_u64 v[32:33], s[8:9], 0, v[32:33]
	v_lshl_add_u64 v[52:53], s[6:7], 0, v[48:49]
	v_lshl_add_u64 v[48:49], s[8:9], 0, v[48:49]
	v_or_b32_e32 v56, 0x280, v144
	v_mov_b32_e32 v57, v145
	v_lshl_add_u64 v[60:61], s[6:7], 0, v[56:57]
	v_lshl_add_u64 v[56:57], s[8:9], 0, v[56:57]
	global_load_dword v37, v[36:37], off
	s_nop 0
	global_load_dword v36, v[32:33], off
	s_nop 0
	global_load_dword v33, v[52:53], off
	global_load_dword v32, v[48:49], off
	s_nop 0
	global_load_dword v49, v[60:61], off
	global_load_dword v48, v[56:57], off
	v_or_b32_e32 v52, 0x2c0, v144
	v_mov_b32_e32 v53, v145
	v_lshl_add_u64 v[56:57], s[6:7], 0, v[52:53]
	v_lshl_add_u64 v[52:53], s[8:9], 0, v[52:53]
	global_load_dword v57, v[56:57], off
	s_nop 0
	global_load_dword v56, v[52:53], off
	s_branch .Lmy_rp2_j
.Lmy_rp2_p2:
	s_waitcnt vmcnt(0)
	v_or_b32_e32 v32, 0x200, v144
	v_mov_b32_e32 v33, v145
	v_or_b32_e32 v48, 0x240, v144
	v_mov_b32_e32 v49, v145
	v_lshl_add_u64 v[36:37], s[6:7], 0, v[32:33]
	v_lshl_add_u64 v[32:33], s[8:9], 0, v[32:33]
	v_lshl_add_u64 v[52:53], s[6:7], 0, v[48:49]
	v_lshl_add_u64 v[48:49], s[8:9], 0, v[48:49]
	v_or_b32_e32 v56, 0x280, v144
	v_mov_b32_e32 v57, v145
	v_lshl_add_u64 v[60:61], s[6:7], 0, v[56:57]
	v_lshl_add_u64 v[56:57], s[8:9], 0, v[56:57]
	v_mov_b32_e32 v37, v232
	s_nop 0
	v_mov_b32_e32 v36, v233
	s_nop 0
	v_mov_b32_e32 v33, v234
	v_mov_b32_e32 v32, v235
	s_nop 0
	v_mov_b32_e32 v49, v236
	v_mov_b32_e32 v48, v237
	v_or_b32_e32 v52, 0x2c0, v144
	v_mov_b32_e32 v53, v145
	v_lshl_add_u64 v[56:57], s[6:7], 0, v[52:53]
	v_lshl_add_u64 v[52:53], s[8:9], 0, v[52:53]
	v_mov_b32_e32 v57, v238
	s_nop 0
	v_mov_b32_e32 v56, v239
.Lmy_rp2_j:
	v_mul_f32_e32 v52, v92, v142
	v_mul_f32_e32 v53, v92, v143
	v_mov_b32_e32 v60, v50
	v_mov_b32_e32 v61, v34
	v_mul_f32_e32 v96, v92, v140
	v_mul_f32_e32 v97, v92, v141
	v_mov_b32_e32 v98, v54
	v_mov_b32_e32 v99, v38
	v_mul_f32_e32 v100, v92, v124
	v_mul_f32_e32 v101, v92, v125
	v_mov_b32_e32 v102, v58
	v_mov_b32_e32 v103, v42
	v_mul_f32_e32 v93, v92, v121
	v_mul_f32_e32 v92, v92, v120
	v_mov_b32_e32 v104, v62
	v_mov_b32_e32 v105, v46
	v_mul_f32_e32 v52, v60, v52
	v_mul_f32_e32 v53, v61, v53
	v_mul_f32_e32 v60, v98, v96
	v_mul_f32_e32 v61, v99, v97
	v_mul_f32_e32 v96, v102, v100
	v_mul_f32_e32 v97, v103, v101
	v_mul_f32_e32 v92, v104, v92
	v_mul_f32_e32 v93, v105, v93
	s_waitcnt vmcnt(7)
	v_mov_b32_e32 v100, v37
	s_waitcnt vmcnt(6)
	v_mul_f32_e32 v98, v52, v36
	v_mul_f32_e32 v99, v53, v37
	v_mov_b32_e32 v101, v36
	s_waitcnt vmcnt(4)
	v_mul_f32_e32 v102, v60, v32
	v_mul_f32_e32 v103, v61, v33
	v_mov_b32_e32 v36, v33
	v_mov_b32_e32 v37, v32
	s_waitcnt vmcnt(2)
	v_mul_f32_e32 v104, v96, v48
	v_mul_f32_e32 v105, v97, v49
	v_mov_b32_e32 v32, v49
	v_mov_b32_e32 v33, v48
	s_waitcnt vmcnt(1)
	v_mov_b32_e32 v106, v57
	s_waitcnt vmcnt(0)
	v_mov_b32_e32 v107, v56
	v_mul_f32_e32 v106, v92, v106
	v_mul_f32_e32 v107, v93, v107
	v_mul_f32_e32 v48, v92, v56
	v_mul_f32_e32 v49, v93, v57
	v_mul_f32_e32 v52, v52, v100
	v_mul_f32_e32 v53, v53, v101
	v_mul_f32_e32 v56, v60, v36
	v_mul_f32_e32 v57, v61, v37
	v_mul_f32_e32 v60, v96, v32
	v_mul_f32_e32 v61, v97, v33
	s_cmp_lg_u32 s89, 0
	s_cbranch_scc1 .Lmy_rp3_p2
	v_or_b32_e32 v32, 0x300, v144
	v_mov_b32_e32 v33, v145
	v_or_b32_e32 v92, 0x340, v144
	v_mov_b32_e32 v93, v145
	v_lshl_add_u64 v[36:37], s[6:7], 0, v[32:33]
	v_lshl_add_u64 v[96:97], s[6:7], 0, v[92:93]
	v_lshl_add_u64 v[92:93], s[8:9], 0, v[92:93]
	v_or_b32_e32 v100, 0x380, v144
	v_mov_b32_e32 v101, v145
	v_lshl_add_u64 v[32:33], s[8:9], 0, v[32:33]
	v_lshl_add_u64 v[112:113], s[6:7], 0, v[100:101]
	v_lshl_add_u64 v[100:101], s[8:9], 0, v[100:101]
	global_load_dword v114, v[36:37], off
	global_load_dword v115, v[32:33], off
	s_nop 0
	global_load_dword v96, v[96:97], off
	s_nop 0
	global_load_dword v97, v[92:93], off
	s_nop 0
	global_load_dword v92, v[112:113], off
	global_load_dword v93, v[100:101], off
	v_or_b32_e32 v32, 0x3c0, v144
	v_mov_b32_e32 v33, v145
	v_lshl_add_u64 v[36:37], s[6:7], 0, v[32:33]
	v_lshl_add_u64 v[32:33], s[8:9], 0, v[32:33]
	global_load_dword v112, v[36:37], off
	global_load_dword v113, v[32:33], off
	s_branch .Lmy_rp3_j
.Lmy_rp3_p2:
	s_waitcnt vmcnt(0)
	v_or_b32_e32 v32, 0x300, v144
	v_mov_b32_e32 v33, v145
	v_or_b32_e32 v92, 0x340, v144
	v_mov_b32_e32 v93, v145
	v_lshl_add_u64 v[36:37], s[6:7], 0, v[32:33]
	v_lshl_add_u64 v[96:97], s[6:7], 0, v[92:93]
	v_lshl_add_u64 v[92:93], s[8:9], 0, v[92:93]
	v_or_b32_e32 v100, 0x380, v144
	v_mov_b32_e32 v101, v145
	v_lshl_add_u64 v[32:33], s[8:9], 0, v[32:33]
	v_lshl_add_u64 v[112:113], s[6:7], 0, v[100:101]
	v_lshl_add_u64 v[100:101], s[8:9], 0, v[100:101]
	v_mov_b32_e32 v114, v240
	v_mov_b32_e32 v115, v241
	s_nop 0
	v_mov_b32_e32 v96, v242
	s_nop 0
	v_mov_b32_e32 v97, v243
	s_nop 0
	v_mov_b32_e32 v92, v248
	v_mov_b32_e32 v93, v249
	v_or_b32_e32 v32, 0x3c0, v144
	v_mov_b32_e32 v33, v145
	v_lshl_add_u64 v[36:37], s[6:7], 0, v[32:33]
	v_lshl_add_u64 v[32:33], s[8:9], 0, v[32:33]
	v_mov_b32_e32 v112, v250
	v_mov_b32_e32 v113, v251
.Lmy_rp3_j:
	v_mov_b32_e32 v32, v143
	v_mov_b32_e32 v33, v142
	v_mov_b32_e32 v50, v35
	v_mov_b32_e32 v34, v141
	v_mov_b32_e32 v35, v140
	v_mov_b32_e32 v54, v39
	v_mov_b32_e32 v36, v125
	v_mov_b32_e32 v37, v124
	v_mov_b32_e32 v38, v121
	v_mov_b32_e32 v39, v120
	v_mul_f32_e32 v116, v88, v32
	v_mul_f32_e32 v117, v88, v33
	v_mov_b32_e32 v58, v43
	v_mov_b32_e32 v62, v47
	v_mul_f32_e32 v118, v88, v34
	v_mul_f32_e32 v119, v88, v35
	v_mul_f32_e32 v122, v88, v36
	v_mul_f32_e32 v123, v88, v37
	v_mul_f32_e32 v89, v88, v39
	v_mul_f32_e32 v88, v88, v38
	v_mul_f32_e32 v50, v50, v116
	v_mul_f32_e32 v51, v51, v117
	v_mul_f32_e32 v54, v54, v118
	v_mul_f32_e32 v55, v55, v119
	v_mul_f32_e32 v58, v58, v122
	v_mul_f32_e32 v59, v59, v123
	v_mul_f32_e32 v62, v62, v88
	v_mul_f32_e32 v63, v63, v89
	v_mov_b32_e32 v42, v52
	v_mov_b32_e32 v100, v60
	v_mov_b32_e32 v46, v56
	s_waitcnt vmcnt(7)
	v_mov_b32_e32 v117, v114
	s_waitcnt vmcnt(6)
	v_mov_b32_e32 v116, v115
	v_mul_f32_e32 v88, v50, v114
	v_mul_f32_e32 v89, v51, v115
	v_mul_f32_e32 v50, v50, v116
	v_mul_f32_e32 v51, v51, v117
	s_waitcnt vmcnt(3)
	v_mov_b32_e32 v123, v92
	s_waitcnt vmcnt(2)
	v_mov_b32_e32 v122, v93
	v_mul_f32_e32 v114, v54, v96
	v_mul_f32_e32 v115, v55, v97
	v_mov_b32_e32 v118, v97
	v_mov_b32_e32 v119, v96
	v_mul_f32_e32 v96, v58, v92
	v_mul_f32_e32 v97, v59, v93
	v_mul_f32_e32 v58, v58, v122
	v_mul_f32_e32 v59, v59, v123
	v_mov_b32_e32 v43, v51
	v_pk_mov_b32 v[50:51], v[52:53], v[50:51] op_sel:[1,0]
	v_mul_f32_e32 v54, v54, v118
	v_mul_f32_e32 v55, v55, v119
	v_mov_b32_e32 v101, v59
	v_pk_mov_b32 v[58:59], v[60:61], v[58:59] op_sel:[1,0]
	v_add_f32_e32 v42, v42, v50
	v_add_f32_e32 v43, v43, v51
	v_mov_b32_e32 v47, v55
	v_pk_mov_b32 v[54:55], v[56:57], v[54:55] op_sel:[1,0]
	v_add_f32_e32 v50, v100, v58
	v_add_f32_e32 v51, v101, v59
	v_mul_f32_e32 v100, v64, v42
	v_mul_f32_e32 v101, v64, v43
	s_waitcnt vmcnt(0)
	v_mov_b32_e32 v42, v113
	v_mov_b32_e32 v43, v112
	v_mul_f32_e32 v92, v62, v112
	v_mul_f32_e32 v93, v63, v113
	v_pk_mov_b32 v[126:127], v[98:99], v[88:89] op_sel:[1,0]
	v_mov_b32_e32 v99, v89
	v_pk_mov_b32 v[88:89], v[102:103], v[114:115] op_sel:[1,0]
	v_mov_b32_e32 v103, v115
	v_add_f32_e32 v46, v46, v54
	v_add_f32_e32 v47, v47, v55
	v_mul_f32_e32 v42, v62, v42
	v_mul_f32_e32 v43, v63, v43
	v_pk_mov_b32 v[114:115], v[104:105], v[96:97] op_sel:[1,0]
	v_mov_b32_e32 v105, v97
	v_pk_mov_b32 v[96:97], v[48:49], v[92:93] op_sel:[1,0]
	v_mov_b32_e32 v49, v93
	v_add_f32_e64 v52, v88, -v102
	v_add_f32_e64 v53, v89, -v103
	v_mul_f32_e32 v102, v64, v46
	v_mul_f32_e32 v103, v64, v47
	v_mov_b32_e32 v46, v106
	v_mov_b32_e32 v47, v43
	v_pk_mov_b32 v[42:43], v[106:107], v[42:43] op_sel:[1,0]
	v_add_f32_e64 v92, v126, -v98
	v_add_f32_e64 v93, v127, -v99
	v_add_f32_e64 v56, v114, -v104
	v_add_f32_e64 v57, v115, -v105
	v_add_f32_e64 v48, v96, -v48
	v_add_f32_e64 v49, v97, -v49
	v_add_f32_e32 v42, v46, v42
	v_add_f32_e32 v43, v47, v43
	v_mul_f32_e32 v88, v64, v92
	v_mul_f32_e32 v89, v64, v93
	v_mul_f32_e32 v92, v64, v52
	v_mul_f32_e32 v93, v64, v53
	v_mul_f32_e32 v96, v64, v56
	v_mul_f32_e32 v97, v64, v57
	v_mul_f32_e32 v104, v64, v50
	v_mul_f32_e32 v105, v64, v51
	v_mul_f32_e32 v98, v64, v48
	v_mul_f32_e32 v99, v64, v49
	v_mul_f32_e32 v106, v64, v42
	v_mul_f32_e32 v107, v64, v43
	s_cmp_lg_u32 s89, 0
	s_cbranch_scc1 .Lmy_rp4_p2
	v_or_b32_e32 v42, 0x1000, v144
	v_mov_b32_e32 v43, v145
	v_or_b32_e32 v48, 0x1040, v144
	v_mov_b32_e32 v49, v145
	v_lshl_add_u64 v[46:47], s[6:7], 0, v[42:43]
	v_lshl_add_u64 v[42:43], s[8:9], 0, v[42:43]
	v_lshl_add_u64 v[50:51], s[6:7], 0, v[48:49]
	v_lshl_add_u64 v[48:49], s[8:9], 0, v[48:49]
	v_or_b32_e32 v52, 0x1080, v144
	v_mov_b32_e32 v53, v145
	v_lshl_add_u64 v[54:55], s[6:7], 0, v[52:53]
	v_lshl_add_u64 v[52:53], s[8:9], 0, v[52:53]
	global_load_dword v47, v[46:47], off
	s_nop 0
	global_load_dword v46, v[42:43], off
	s_nop 0
	global_load_dword v43, v[50:51], off
	global_load_dword v42, v[48:49], off
	s_nop 0
	global_load_dword v49, v[54:55], off
	global_load_dword v48, v[52:53], off
	v_or_b32_e32 v50, 0x10c0, v144
	v_mov_b32_e32 v51, v145
	v_lshl_add_u64 v[52:53], s[6:7], 0, v[50:51]
	v_lshl_add_u64 v[50:51], s[8:9], 0, v[50:51]
	global_load_dword v53, v[52:53], off
	s_nop 0
	global_load_dword v52, v[50:51], off
	s_branch .Lmy_rp4_j
.Lmy_rp4_p2:
	s_waitcnt vmcnt(0)
	v_or_b32_e32 v42, 0x1000, v144
	v_mov_b32_e32 v43, v145
	v_or_b32_e32 v48, 0x1040, v144
	v_mov_b32_e32 v49, v145
	v_lshl_add_u64 v[46:47], s[6:7], 0, v[42:43]
	v_lshl_add_u64 v[42:43], s[8:9], 0, v[42:43]
	v_lshl_add_u64 v[50:51], s[6:7], 0, v[48:49]
	v_lshl_add_u64 v[48:49], s[8:9], 0, v[48:49]
	v_or_b32_e32 v52, 0x1080, v144
	v_mov_b32_e32 v53, v145
	v_lshl_add_u64 v[54:55], s[6:7], 0, v[52:53]
	v_lshl_add_u64 v[52:53], s[8:9], 0, v[52:53]
	v_mov_b32_e32 v47, v252
	s_nop 0
	v_mov_b32_e32 v46, v253
	s_nop 0
	v_mov_b32_e32 v43, v254
	v_mov_b32_e32 v42, v255
	s_nop 0
	v_mov_b32_e32 v49, v66
	v_mov_b32_e32 v48, v67
	v_or_b32_e32 v50, 0x10c0, v144
	v_mov_b32_e32 v51, v145
	v_lshl_add_u64 v[52:53], s[6:7], 0, v[50:51]
	v_lshl_add_u64 v[50:51], s[8:9], 0, v[50:51]
	v_mov_b32_e32 v53, v68
	s_nop 0
	v_mov_b32_e32 v52, v69
.Lmy_rp4_j:
	v_mul_f32_e32 v50, v108, v142
	v_mul_f32_e32 v51, v108, v143
	v_mov_b32_e32 v1, v4
	v_mul_f32_e32 v54, v108, v140
	v_mul_f32_e32 v55, v108, v141
	v_mov_b32_e32 v9, v12
	v_mul_f32_e32 v56, v108, v124
	v_mul_f32_e32 v57, v108, v125
	v_mov_b32_e32 v25, v16
	v_mul_f32_e32 v58, v108, v120
	v_mul_f32_e32 v59, v108, v121
	v_mov_b32_e32 v29, v20
	v_mul_f32_e32 v0, v0, v50
	v_mul_f32_e32 v1, v1, v51
	v_mul_f32_e32 v8, v8, v54
	v_mul_f32_e32 v9, v9, v55
	v_mul_f32_e32 v24, v24, v56
	v_mul_f32_e32 v25, v25, v57
	v_mul_f32_e32 v28, v28, v58
	v_mul_f32_e32 v29, v29, v59
	s_waitcnt vmcnt(7)
	v_mov_b32_e32 v54, v47
	s_waitcnt vmcnt(6)
	v_mov_b32_e32 v55, v46
	s_waitcnt vmcnt(5)
	v_mov_b32_e32 v56, v43
	s_waitcnt vmcnt(4)
	v_mov_b32_e32 v57, v42
	s_waitcnt vmcnt(3)
	v_mov_b32_e32 v58, v49
	s_waitcnt vmcnt(2)
	v_mov_b32_e32 v59, v48
	v_mul_f32_e32 v50, v0, v46
	v_mul_f32_e32 v51, v1, v47
	v_mul_f32_e32 v46, v8, v42
	v_mul_f32_e32 v47, v9, v43
	v_mul_f32_e32 v42, v24, v48
	v_mul_f32_e32 v43, v25, v49
	s_waitcnt vmcnt(1)
	v_mov_b32_e32 v60, v53
	s_waitcnt vmcnt(0)
	v_mov_b32_e32 v61, v52
	v_mul_f32_e32 v48, v28, v52
	v_mul_f32_e32 v49, v29, v53
	v_mul_f32_e32 v0, v0, v54
	v_mul_f32_e32 v1, v1, v55
	v_mul_f32_e32 v8, v8, v56
	v_mul_f32_e32 v9, v9, v57
	v_mul_f32_e32 v24, v24, v58
	v_mul_f32_e32 v25, v25, v59
	v_mul_f32_e32 v28, v28, v60
	v_mul_f32_e32 v29, v29, v61
	s_cmp_lg_u32 s89, 0
	s_cbranch_scc1 .Lmy_rp5_p2
	v_or_b32_e32 v52, 0x1100, v144
	v_mov_b32_e32 v53, v145
	v_lshl_add_u64 v[54:55], s[6:7], 0, v[52:53]
	v_lshl_add_u64 v[52:53], s[8:9], 0, v[52:53]
	global_load_dword v60, v[54:55], off
	global_load_dword v61, v[52:53], off
	v_or_b32_e32 v52, 0x1140, v144
	v_mov_b32_e32 v53, v145
	v_or_b32_e32 v56, 0x1180, v144
	v_mov_b32_e32 v57, v145
	v_lshl_add_u64 v[54:55], s[6:7], 0, v[52:53]
	v_lshl_add_u64 v[52:53], s[8:9], 0, v[52:53]
	v_lshl_add_u64 v[58:59], s[6:7], 0, v[56:57]
	v_lshl_add_u64 v[56:57], s[8:9], 0, v[56:57]
	global_load_dword v62, v[54:55], off
	global_load_dword v63, v[52:53], off
	s_nop 0
	global_load_dword v58, v[58:59], off
	s_nop 0
	global_load_dword v56, v[56:57], off
	v_or_b32_e32 v52, 0x11c0, v144
	v_mov_b32_e32 v53, v145
	v_lshl_add_u64 v[54:55], s[6:7], 0, v[52:53]
	v_lshl_add_u64 v[52:53], s[8:9], 0, v[52:53]
	global_load_dword v57, v[54:55], off
	global_load_dword v59, v[52:53], off
	s_branch .Lmy_rp5_j
.Lmy_rp5_p2:
	s_waitcnt vmcnt(0)
	v_or_b32_e32 v52, 0x1100, v144
	v_mov_b32_e32 v53, v145
	v_lshl_add_u64 v[54:55], s[6:7], 0, v[52:53]
	v_lshl_add_u64 v[52:53], s[8:9], 0, v[52:53]
	v_mov_b32_e32 v60, v71
	v_mov_b32_e32 v61, v74
	v_or_b32_e32 v52, 0x1140, v144
	v_mov_b32_e32 v53, v145
	v_or_b32_e32 v56, 0x1180, v144
	v_mov_b32_e32 v57, v145
	v_lshl_add_u64 v[54:55], s[6:7], 0, v[52:53]
	v_lshl_add_u64 v[52:53], s[8:9], 0, v[52:53]
	v_lshl_add_u64 v[58:59], s[6:7], 0, v[56:57]
	v_lshl_add_u64 v[56:57], s[8:9], 0, v[56:57]
	v_mov_b32_e32 v62, v75
	v_mov_b32_e32 v63, v160
	s_nop 0
	v_mov_b32_e32 v58, v161
	s_nop 0
	v_mov_b32_e32 v56, v162
	v_or_b32_e32 v52, 0x11c0, v144
	v_mov_b32_e32 v53, v145
	v_lshl_add_u64 v[54:55], s[6:7], 0, v[52:53]
	v_lshl_add_u64 v[52:53], s[8:9], 0, v[52:53]
	v_mov_b32_e32 v57, v185
	v_mov_b32_e32 v59, v186
.Lmy_rp5_j:
	v_mov_b32_e32 v52, v51
	v_mov_b32_e32 v40, v1
	v_mov_b32_e32 v44, v9
	v_mov_b32_e32 v4, v25
	v_mov_b32_e32 v16, v49
	v_mov_b32_e32 v20, v47
	v_mov_b32_e32 v54, v43
	v_mov_b32_e32 v12, v29
	s_waitcnt vmcnt(7)
	v_mul_f32_e32 v53, v41, v60
	s_waitcnt vmcnt(6)
	v_mul_f32_e32 v51, v21, v61
	v_mul_f32_e32 v41, v41, v61
	v_mul_f32_e32 v1, v21, v60
	v_add_f32_e32 v0, v0, v40
	v_add_f32_e32 v1, v1, v41
	s_waitcnt vmcnt(5)
	v_mul_f32_e32 v21, v45, v62
	s_waitcnt vmcnt(4)
	v_mul_f32_e32 v45, v45, v63
	v_mul_f32_e32 v9, v109, v62
	s_waitcnt vmcnt(3)
	v_mul_f32_e32 v55, v5, v58
	s_waitcnt vmcnt(2)
	v_mul_f32_e32 v49, v17, v56
	v_mul_f32_e32 v5, v5, v56
	v_mul_f32_e32 v25, v17, v58
	v_mul_f32_e32 v47, v109, v63
	s_waitcnt vmcnt(0)
	v_mul_f32_e32 v56, v110, v59
	v_mul_f32_e32 v17, v13, v57
	v_mul_f32_e32 v13, v13, v59
	v_mul_f32_e32 v29, v110, v57
	v_add_f32_e32 v8, v8, v44
	v_add_f32_e32 v9, v9, v45
	v_mov_b32_e32 v43, v49
	v_add_f32_e32 v4, v24, v4
	v_add_f32_e32 v5, v25, v5
	v_mov_b32_e32 v49, v56
	v_add_f32_e32 v12, v28, v12
	v_add_f32_e32 v13, v29, v13
	v_add_f32_e64 v24, v52, -v50
	v_add_f32_e64 v25, v53, -v51
	v_mul_f32_e32 v116, v64, v0
	v_mul_f32_e32 v117, v64, v1
	v_add_f32_e64 v0, v20, -v46
	v_add_f32_e64 v1, v21, -v47
	v_mul_f32_e32 v118, v64, v8
	v_mul_f32_e32 v119, v64, v9
	v_add_f32_e64 v8, v54, -v42
	v_add_f32_e64 v9, v55, -v43
	v_mul_f32_e32 v122, v64, v4
	v_mul_f32_e32 v123, v64, v5
	v_add_f32_e64 v4, v16, -v48
	v_add_f32_e64 v5, v17, -v49
	v_mul_f32_e32 v108, v64, v24
	v_mul_f32_e32 v109, v64, v25
	v_mul_f32_e32 v110, v64, v0
	v_mul_f32_e32 v111, v64, v1
	v_mul_f32_e32 v112, v64, v8
	v_mul_f32_e32 v113, v64, v9
	v_mul_f32_e32 v114, v64, v4
	v_mul_f32_e32 v115, v64, v5
	v_mul_f32_e32 v126, v64, v12
	v_mul_f32_e32 v127, v64, v13
	s_cmp_lg_u32 s89, 0
	s_cbranch_scc1 .Lmy_rp6_p2
	v_or_b32_e32 v0, 0x1200, v144
	v_mov_b32_e32 v1, v145
	v_or_b32_e32 v8, 0x1240, v144
	v_mov_b32_e32 v9, v145
	v_lshl_add_u64 v[4:5], s[6:7], 0, v[0:1]
	v_lshl_add_u64 v[0:1], s[8:9], 0, v[0:1]
	v_lshl_add_u64 v[12:13], s[6:7], 0, v[8:9]
	v_lshl_add_u64 v[8:9], s[8:9], 0, v[8:9]
	v_or_b32_e32 v16, 0x1280, v144
	v_mov_b32_e32 v17, v145
	v_lshl_add_u64 v[20:21], s[6:7], 0, v[16:17]
	v_lshl_add_u64 v[16:17], s[8:9], 0, v[16:17]
	global_load_dword v5, v[4:5], off
	s_nop 0
	global_load_dword v4, v[0:1], off
	s_nop 0
	global_load_dword v1, v[12:13], off
	global_load_dword v0, v[8:9], off
	s_nop 0
	global_load_dword v9, v[20:21], off
	global_load_dword v8, v[16:17], off
	v_or_b32_e32 v12, 0x12c0, v144
	v_mov_b32_e32 v13, v145
	v_lshl_add_u64 v[16:17], s[6:7], 0, v[12:13]
	v_lshl_add_u64 v[12:13], s[8:9], 0, v[12:13]
	global_load_dword v17, v[16:17], off
	s_nop 0
	global_load_dword v16, v[12:13], off
	s_branch .Lmy_rp6_j
.Lmy_rp6_p2:
	s_waitcnt vmcnt(0)
	v_or_b32_e32 v0, 0x1200, v144
	v_mov_b32_e32 v1, v145
	v_or_b32_e32 v8, 0x1240, v144
	v_mov_b32_e32 v9, v145
	v_lshl_add_u64 v[4:5], s[6:7], 0, v[0:1]
	v_lshl_add_u64 v[0:1], s[8:9], 0, v[0:1]
	v_lshl_add_u64 v[12:13], s[6:7], 0, v[8:9]
	v_lshl_add_u64 v[8:9], s[8:9], 0, v[8:9]
	v_or_b32_e32 v16, 0x1280, v144
	v_mov_b32_e32 v17, v145
	v_lshl_add_u64 v[20:21], s[6:7], 0, v[16:17]
	v_lshl_add_u64 v[16:17], s[8:9], 0, v[16:17]
	v_mov_b32_e32 v5, v187
	s_nop 0
	v_mov_b32_e32 v4, v207
	s_nop 0
	v_mov_b32_e32 v1, v212
	v_mov_b32_e32 v0, v213
	s_nop 0
	v_mov_b32_e32 v9, v214
	v_mov_b32_e32 v8, v216
	v_or_b32_e32 v12, 0x12c0, v144
	v_mov_b32_e32 v13, v145
	v_lshl_add_u64 v[16:17], s[6:7], 0, v[12:13]
	v_lshl_add_u64 v[12:13], s[8:9], 0, v[12:13]
	v_mov_b32_e32 v17, v218
	s_nop 0
	v_mov_b32_e32 v16, v220
.Lmy_rp6_j:
	v_mul_f32_e32 v12, v148, v142
	v_mul_f32_e32 v13, v148, v143
	v_mov_b32_e32 v20, v2
	v_mov_b32_e32 v21, v6
	v_mul_f32_e32 v24, v148, v140
	v_mul_f32_e32 v25, v148, v141
	v_mov_b32_e32 v28, v10
	v_mov_b32_e32 v29, v14
	v_mul_f32_e32 v40, v148, v124
	v_mul_f32_e32 v41, v148, v125
	v_mov_b32_e32 v42, v26
	v_mov_b32_e32 v43, v18
	v_mul_f32_e32 v44, v148, v120
	v_mul_f32_e32 v45, v148, v121
	v_mov_b32_e32 v46, v30
	v_mov_b32_e32 v47, v22
	v_mul_f32_e32 v12, v20, v12
	v_mul_f32_e32 v13, v21, v13
	v_mul_f32_e32 v20, v28, v24
	v_mul_f32_e32 v21, v29, v25
	v_mul_f32_e32 v24, v42, v40
	v_mul_f32_e32 v25, v43, v41
	v_mul_f32_e32 v28, v46, v44
	v_mul_f32_e32 v29, v47, v45
	s_waitcnt vmcnt(7)
	v_mov_b32_e32 v42, v5
	s_waitcnt vmcnt(6)
	v_mov_b32_e32 v43, v4
	s_waitcnt vmcnt(5)
	v_mov_b32_e32 v44, v1
	s_waitcnt vmcnt(4)
	v_mov_b32_e32 v45, v0
	s_waitcnt vmcnt(3)
	v_mov_b32_e32 v46, v9
	s_waitcnt vmcnt(2)
	v_mov_b32_e32 v47, v8
	v_mul_f32_e32 v40, v12, v4
	v_mul_f32_e32 v41, v13, v5
	v_mul_f32_e32 v4, v20, v0
	v_mul_f32_e32 v5, v21, v1
	v_mul_f32_e32 v0, v24, v8
	v_mul_f32_e32 v1, v25, v9
	s_waitcnt vmcnt(1)
	v_mov_b32_e32 v48, v17
	s_waitcnt vmcnt(0)
	v_mov_b32_e32 v49, v16
	v_mul_f32_e32 v8, v28, v16
	v_mul_f32_e32 v9, v29, v17
	v_mul_f32_e32 v12, v12, v42
	v_mul_f32_e32 v13, v13, v43
	v_mul_f32_e32 v16, v20, v44
	v_mul_f32_e32 v17, v21, v45
	v_mul_f32_e32 v20, v24, v46
	v_mul_f32_e32 v21, v25, v47
	v_mul_f32_e32 v24, v28, v48
	v_mul_f32_e32 v25, v29, v49
	s_cmp_lg_u32 s89, 0
	s_cbranch_scc1 .Lmy_rp7_p2
	v_or_b32_e32 v28, 0x1300, v144
	v_mov_b32_e32 v29, v145
	v_or_b32_e32 v44, 0x1340, v144
	v_mov_b32_e32 v45, v145
	v_lshl_add_u64 v[42:43], s[6:7], 0, v[28:29]
	v_lshl_add_u64 v[28:29], s[8:9], 0, v[28:29]
	v_lshl_add_u64 v[46:47], s[6:7], 0, v[44:45]
	v_lshl_add_u64 v[44:45], s[8:9], 0, v[44:45]
	v_or_b32_e32 v48, 0x1380, v144
	v_mov_b32_e32 v49, v145
	v_or_b32_e32 v144, 0x13c0, v144
	v_lshl_add_u64 v[50:51], s[6:7], 0, v[48:49]
	v_lshl_add_u64 v[48:49], s[8:9], 0, v[48:49]
	global_load_dword v42, v[42:43], off
	s_nop 0
	global_load_dword v43, v[28:29], off
	s_nop 0
	global_load_dword v28, v[46:47], off
	global_load_dword v29, v[44:45], off
	s_nop 0
	global_load_dword v44, v[50:51], off
	global_load_dword v45, v[48:49], off
	v_lshl_add_u64 v[46:47], s[6:7], 0, v[144:145]
	v_lshl_add_u64 v[48:49], s[8:9], 0, v[144:145]
	global_load_dword v46, v[46:47], off
	s_nop 0
	global_load_dword v47, v[48:49], off
	s_branch .Lmy_rp7_j
.Lmy_rp7_p2:
	s_waitcnt vmcnt(0)
	v_or_b32_e32 v28, 0x1300, v144
	v_mov_b32_e32 v29, v145
	v_or_b32_e32 v44, 0x1340, v144
	v_mov_b32_e32 v45, v145
	v_lshl_add_u64 v[42:43], s[6:7], 0, v[28:29]
	v_lshl_add_u64 v[28:29], s[8:9], 0, v[28:29]
	v_lshl_add_u64 v[46:47], s[6:7], 0, v[44:45]
	v_lshl_add_u64 v[44:45], s[8:9], 0, v[44:45]
	v_or_b32_e32 v48, 0x1380, v144
	v_mov_b32_e32 v49, v145
	v_or_b32_e32 v144, 0x13c0, v144
	v_lshl_add_u64 v[50:51], s[6:7], 0, v[48:49]
	v_lshl_add_u64 v[48:49], s[8:9], 0, v[48:49]
	v_mov_b32_e32 v42, v222
	s_nop 0
	v_mov_b32_e32 v43, v224
	s_nop 0
	v_mov_b32_e32 v28, v226
	v_mov_b32_e32 v29, v228
	s_nop 0
	v_mov_b32_e32 v44, v230
	v_mov_b32_e32 v45, v231
	v_lshl_add_u64 v[46:47], s[6:7], 0, v[144:145]
	v_lshl_add_u64 v[48:49], s[8:9], 0, v[144:145]
	v_mov_b32_e32 v46, v244
	s_nop 0
	v_mov_b32_e32 v47, v245
.Lmy_rp7_j:
	v_mul_f32_e32 v32, v32, v146
	v_mul_f32_e32 v33, v33, v146
	v_mov_b32_e32 v2, v7
	v_mul_f32_e32 v34, v34, v146
	v_mul_f32_e32 v35, v35, v146
	v_mov_b32_e32 v10, v15
	v_mul_f32_e32 v36, v36, v146
	v_mul_f32_e32 v37, v37, v146
	v_mov_b32_e32 v26, v19
	v_mul_f32_e32 v38, v38, v146
	v_mul_f32_e32 v39, v39, v146
	v_mov_b32_e32 v30, v23
	v_mul_f32_e32 v2, v2, v32
	v_mul_f32_e32 v3, v3, v33
	v_mul_f32_e32 v10, v10, v34
	v_mul_f32_e32 v11, v11, v35
	v_mul_f32_e32 v26, v26, v36
	v_mul_f32_e32 v27, v27, v37
	v_mul_f32_e32 v30, v30, v38
	v_mul_f32_e32 v31, v31, v39
	v_mov_b32_e32 v6, v12
	v_mov_b32_e32 v14, v16
	v_mov_b32_e32 v18, v20
	v_mov_b32_e32 v22, v24
	s_waitcnt vmcnt(7)
	v_mov_b32_e32 v35, v42
	s_waitcnt vmcnt(6)
	v_mul_f32_e32 v32, v2, v42
	v_mul_f32_e32 v33, v3, v43
	v_mov_b32_e32 v34, v43
	s_waitcnt vmcnt(4)
	v_mul_f32_e32 v36, v10, v28
	v_mul_f32_e32 v37, v11, v29
	v_mov_b32_e32 v38, v29
	v_mov_b32_e32 v39, v28
	s_waitcnt vmcnt(2)
	v_mul_f32_e32 v28, v26, v44
	v_mul_f32_e32 v29, v27, v45
	v_mov_b32_e32 v42, v45
	v_mov_b32_e32 v43, v44
	s_waitcnt vmcnt(0)
	v_mov_b32_e32 v48, v47
	v_mov_b32_e32 v49, v46
	v_mul_f32_e32 v44, v30, v46
	v_mul_f32_e32 v45, v31, v47
	v_pk_mov_b32 v[46:47], v[40:41], v[32:33] op_sel:[1,0]
	v_mov_b32_e32 v41, v33
	v_mul_f32_e32 v2, v2, v34
	v_mul_f32_e32 v3, v3, v35
	v_pk_mov_b32 v[32:33], v[4:5], v[36:37] op_sel:[1,0]
	v_mov_b32_e32 v5, v37
	v_mul_f32_e32 v10, v10, v38
	v_mul_f32_e32 v11, v11, v39
	v_pk_mov_b32 v[34:35], v[0:1], v[28:29] op_sel:[1,0]
	v_mov_b32_e32 v1, v29
	v_mul_f32_e32 v26, v26, v42
	v_mul_f32_e32 v27, v27, v43
	v_mul_f32_e32 v30, v30, v48
	v_mul_f32_e32 v31, v31, v49
	v_pk_mov_b32 v[28:29], v[8:9], v[44:45] op_sel:[1,0]
	v_mov_b32_e32 v9, v45
	v_mov_b32_e32 v7, v3
	v_pk_mov_b32 v[2:3], v[12:13], v[2:3] op_sel:[1,0]
	v_add_f32_e64 v4, v32, -v4
	v_add_f32_e64 v5, v33, -v5
	v_mov_b32_e32 v15, v11
	v_pk_mov_b32 v[10:11], v[16:17], v[10:11] op_sel:[1,0]
	v_add_f32_e64 v0, v34, -v0
	v_add_f32_e64 v1, v35, -v1
	v_mov_b32_e32 v19, v27
	v_pk_mov_b32 v[12:13], v[20:21], v[26:27] op_sel:[1,0]
	v_mov_b32_e32 v23, v31
	v_pk_mov_b32 v[16:17], v[24:25], v[30:31] op_sel:[1,0]
	v_add_f32_e64 v36, v46, -v40
	v_add_f32_e64 v37, v47, -v41
	v_add_f32_e64 v8, v28, -v8
	v_add_f32_e64 v9, v29, -v9
	v_add_f32_e32 v2, v6, v2
	v_add_f32_e32 v3, v7, v3
	v_mul_f32_e32 v124, v64, v4
	v_mul_f32_e32 v125, v64, v5
	v_add_f32_e32 v4, v14, v10
	v_add_f32_e32 v5, v15, v11
	v_mul_f32_e32 v140, v64, v0
	v_mul_f32_e32 v141, v64, v1
	v_add_f32_e32 v0, v18, v12
	v_add_f32_e32 v1, v19, v13
	v_add_f32_e32 v6, v22, v16
	v_add_f32_e32 v7, v23, v17
	v_mul_f32_e32 v120, v64, v36
	v_mul_f32_e32 v121, v64, v37
	v_mul_f32_e32 v142, v64, v8
	v_mul_f32_e32 v143, v64, v9
	v_mul_f32_e32 v144, v64, v2
	v_mul_f32_e32 v145, v64, v3
	v_mul_f32_e32 v146, v64, v4
	v_mul_f32_e32 v147, v64, v5
	v_mul_f32_e32 v148, v64, v0
	v_mul_f32_e32 v149, v64, v1
	v_mul_f32_e32 v150, v64, v6
	v_mul_f32_e32 v151, v64, v7
	s_and_b64 s[0:1], s[56:57], exec
	s_cselect_b32 s0, s61, 0xba00000
	s_add_u32 s4, s50, s0
	s_addc_u32 s5, s51, 0
	s_lshl_b64 s[0:1], s[54:55], 1
	s_add_u32 s0, s4, s0
	s_addc_u32 s1, s5, s1
	s_lshl_b32 s4, s33, 8
	s_add_u32 s56, s0, s4
	s_addc_u32 s57, s1, 0
	s_cbranch_execnz .LBB0_441
